# no per-phase flips + one static s_setprio 1 for waves 4-7 at kernel entry
# speedup vs baseline: 1.0091x; 1.0021x over previous
_Z10fwd_kernel6Params:
	v_readfirstlane_b32 s98, v0
	s_nop 3
	s_and_b32 s98, s98, 0x3ff
	s_cmp_lt_u32 s98, 0x100
	s_cbranch_scc1 .Lprio_skip
	s_setprio 1
.Lprio_skip:
	s_load_dwordx8 s[88:95], s[0:1], 0xa0
	s_load_dwordx8 s[4:11], s[0:1], 0x80
	s_mov_b32 s70, s2
	v_and_b32_e32 v197, 0x3ff, v0
	s_waitcnt lgkmcnt(0)
	v_writelane_b32 v252, s4, 0
	s_nop 1
	v_writelane_b32 v252, s5, 1
	v_writelane_b32 v252, s6, 2
	v_writelane_b32 v252, s7, 3
	v_writelane_b32 v252, s8, 4
	v_writelane_b32 v252, s9, 5
	v_writelane_b32 v252, s10, 6
	v_writelane_b32 v252, s11, 7
	v_cmp_eq_u32_e64 s[4:5], 0, v197
	s_mov_b64 s[6:7], exec
	s_nop 0
	v_writelane_b32 v252, s4, 8
	s_nop 1
	v_writelane_b32 v252, s5, 9
	s_and_b64 s[4:5], s[6:7], s[4:5]
	s_mov_b64 exec, s[4:5]
	s_cbranch_execz .LBB0_2
	s_add_i32 s4, 0, 0x20000
	v_mov_b32_e32 v1, 0
	v_mov_b32_e32 v2, s4
	s_add_i32 s4, 0, 0x20004
	ds_write_b32 v2, v1
	v_mov_b32_e32 v2, s4
	ds_write_b32 v2, v1
